# layer-0 gate and ffn gate/up conversions back in the prologue (B(0)/G(0) tail sites removed); ffn-down sites kept
# baseline (speedup 1.0000x reference)
.LBB0_23:
	s_waitcnt vmcnt(16)
	v_mov_b32_e32 v1, v208
	s_mov_b32 s37, s2
	s_waitcnt lgkmcnt(0)
	s_barrier
	s_cmpk_gt_i32 s37, 0x7ff
	s_cbranch_scc1 .LBB0_28
	s_ashr_i32 s12, s37, 31
	s_lshr_b32 s12, s12, 28
	s_add_i32 s12, s37, s12
	s_ashr_i32 s13, s12, 4
	v_and_b32_e32 v20, 63, v1
	s_lshl_b32 s28, s13, 6
	v_or_b32_e32 v2, s28, v20
	v_bfe_u32 v23, v1, 4, 1
	v_ashrrev_i32_e32 v26, 6, v1
	v_and_b32_e32 v21, 15, v1
	v_ashrrev_i32_e32 v22, 4, v1
	v_and_or_b32 v1, s13, 2, v23
	s_ashr_i32 s13, s28, 2
	v_lshrrev_b32_e32 v2, 1, v2
	s_andn2_b32 s13, s13, 63
	v_and_b32_e32 v2, 48, v2
	s_and_b32 s12, s12, 0x1fffff0
	v_or3_b32 v2, s13, v2, v21
	s_waitcnt vmcnt(3)
	v_lshlrev_b32_e32 v16, 13, v1
	v_mov_b32_e32 v17, 0
	s_sub_i32 s12, s37, s12
	v_lshl_add_u64 v[4:5], s[6:7], 0, v[16:17]
	v_ashrrev_i32_e32 v3, 31, v2
	v_lshl_add_u64 v[2:3], v[2:3], 2, v[4:5]
	v_lshl_add_u32 v4, s12, 7, v26
	v_ashrrev_i32_e32 v5, 31, v4
	v_lshlrev_b64 v[4:5], 15, v[4:5]
	v_lshl_add_u64 v[2:3], v[2:3], 0, v[4:5]
	s_mov_b32 s30, 0x40000
	v_add_co_u32_e32 v4, vcc, s30, v2
	s_mov_b32 s31, 0x80000
	s_nop 0
	v_addc_co_u32_e32 v5, vcc, 0, v3, vcc
	v_add_co_u32_e32 v6, vcc, s31, v2
	s_mov_b32 s33, 0xc0000
	s_nop 0
	v_addc_co_u32_e32 v7, vcc, 0, v3, vcc
	v_add_co_u32_e32 v8, vcc, s33, v2
	s_mov_b32 s34, 0x100000
	s_nop 0
	v_addc_co_u32_e32 v9, vcc, 0, v3, vcc
	v_add_co_u32_e32 v10, vcc, s34, v2
	s_mov_b32 s35, 0x140000
	s_nop 0
	v_addc_co_u32_e32 v11, vcc, 0, v3, vcc
	v_add_co_u32_e32 v12, vcc, s35, v2
	s_mov_b32 s36, 0x180000
	s_nop 0
	v_addc_co_u32_e32 v13, vcc, 0, v3, vcc
	v_add_co_u32_e32 v14, vcc, s36, v2
	s_mov_b32 s38, 0x1c0000
	s_waitcnt vmcnt(2)
	v_addc_co_u32_e32 v15, vcc, 0, v3, vcc
	v_add_co_u32_e32 v28, vcc, s38, v2
	s_mov_b32 s39, 0x200000
	s_nop 0
	v_addc_co_u32_e32 v29, vcc, 0, v3, vcc
	v_add_co_u32_e32 v30, vcc, s39, v2
	s_mov_b32 s40, 0x240000
	s_nop 0
	v_addc_co_u32_e32 v31, vcc, 0, v3, vcc
	v_add_co_u32_e32 v32, vcc, s40, v2
	s_mov_b32 s41, 0x280000
	s_nop 0
	v_addc_co_u32_e32 v33, vcc, 0, v3, vcc
	v_add_co_u32_e32 v34, vcc, s41, v2
	s_mov_b32 s42, 0x2c0000
	s_nop 0
	v_addc_co_u32_e32 v35, vcc, 0, v3, vcc
	v_add_co_u32_e32 v36, vcc, s42, v2
	s_mov_b32 s43, 0x300000
	s_nop 0
	v_addc_co_u32_e32 v37, vcc, 0, v3, vcc
	v_add_co_u32_e32 v38, vcc, s43, v2
	s_mov_b32 s12, 0x340000
	s_nop 0
	v_addc_co_u32_e32 v39, vcc, 0, v3, vcc
	v_add_co_u32_e32 v40, vcc, s12, v2
	s_mov_b32 s12, 0x380000
	s_nop 0
	v_addc_co_u32_e32 v41, vcc, 0, v3, vcc
	v_add_co_u32_e32 v42, vcc, s12, v2
	s_mov_b32 s12, 0x3c0000
	s_nop 0
	v_addc_co_u32_e32 v43, vcc, 0, v3, vcc
	v_add_co_u32_e32 v44, vcc, s12, v2
	v_lshlrev_b32_e32 v16, 4, v21
	s_nop 0
	v_addc_co_u32_e32 v45, vcc, 0, v3, vcc
	v_lshl_add_u64 v[18:19], s[22:23], 0, v[16:17]
	global_load_dword v2, v[2:3], off nt
	s_nop 0
	global_load_dword v1, v[4:5], off nt
	s_nop 0
	global_load_dword v4, v[6:7], off nt
	global_load_dword v3, v[8:9], off nt
	s_nop 0
	global_load_dword v6, v[10:11], off nt
	global_load_dword v5, v[12:13], off nt
	global_load_dword v8, v[14:15], off nt
	global_load_dword v7, v[28:29], off nt
	s_nop 0
	global_load_dword v10, v[30:31], off nt
	global_load_dword v9, v[32:33], off nt
	global_load_dword v12, v[34:35], off nt
	global_load_dword v11, v[36:37], off nt
	global_load_dword v14, v[38:39], off nt
	global_load_dword v13, v[40:41], off nt
	global_load_dword v16, v[42:43], off nt
	global_load_dword v15, v[44:45], off nt
	s_mov_b64 s[12:13], 0x1378000
	v_lshl_add_u64 v[18:19], v[18:19], 0, s[12:13]
	s_movk_i32 s12, 0x104
	s_lshl_b32 s45, s60, 7
	v_mul_lo_u32 v24, v26, s12
	v_mul_u32_u24_e32 v25, 0x820, v21
	s_lshl_b32 s44, s37, 7
	v_add_u32_e32 v26, s45, v26
	s_mov_b64 s[12:13], 0
	s_branch .LBB0_26

.LBB0_26:
	s_and_b64 s[28:29], s[12:13], exec
	s_cselect_b32 s28, 0x8200, 0
	s_add_i32 s47, s28, 0
	s_add_i32 s46, s37, s60
	s_cmpk_gt_i32 s46, 0x7ff
	v_lshlrev_b32_e32 v27, 2, v20
	s_cselect_b64 s[28:29], -1, 0
	v_add3_u32 v27, s47, v27, v24
	s_and_b64 vcc, exec, s[28:29]
	s_waitcnt vmcnt(15)
	ds_write_b32 v27, v2
	s_waitcnt vmcnt(14)
	ds_write_b32 v27, v1 offset:2080
	s_waitcnt vmcnt(13)
	ds_write_b32 v27, v4 offset:4160
	s_waitcnt vmcnt(12)
	ds_write_b32 v27, v3 offset:6240
	s_waitcnt vmcnt(11)
	ds_write_b32 v27, v6 offset:8320
	s_waitcnt vmcnt(10)
	ds_write_b32 v27, v5 offset:10400
	s_waitcnt vmcnt(9)
	ds_write_b32 v27, v8 offset:12480
	s_waitcnt vmcnt(8)
	ds_write_b32 v27, v7 offset:14560
	s_waitcnt vmcnt(7)
	ds_write_b32 v27, v10 offset:16640
	s_waitcnt vmcnt(6)
	ds_write_b32 v27, v9 offset:18720
	s_waitcnt vmcnt(5)
	ds_write_b32 v27, v12 offset:20800
	s_waitcnt vmcnt(4)
	ds_write_b32 v27, v11 offset:22880
	s_waitcnt vmcnt(3)
	ds_write_b32 v27, v14 offset:24960
	s_waitcnt vmcnt(2)
	ds_write_b32 v27, v13 offset:27040
	s_waitcnt vmcnt(1)
	ds_write_b32 v27, v16 offset:29120
	s_waitcnt vmcnt(0)
	ds_write_b32 v27, v15 offset:31200
	s_cbranch_vccnz .LBB0_25
	s_ashr_i32 s48, s46, 31
	s_lshr_b32 s48, s48, 28
	s_add_i32 s48, s46, s48
	s_ashr_i32 s48, s48, 4
	s_lshl_b32 s49, s48, 6
	v_or_b32_e32 v1, s49, v20
	s_ashr_i32 s49, s49, 2
	v_lshrrev_b32_e32 v1, 1, v1
	v_and_or_b32 v3, s48, 2, v23
	s_andn2_b32 s49, s49, 63
	v_and_b32_e32 v1, 48, v1
	v_or3_b32 v2, s49, v1, v21
	v_lshlrev_b32_e32 v16, 13, v3
	v_lshl_add_u64 v[4:5], s[6:7], 0, v[16:17]
	v_ashrrev_i32_e32 v3, 31, v2
	v_add_u32_e32 v1, s44, v26
	s_lshl_b32 s48, s48, 11
	v_lshl_add_u64 v[2:3], v[2:3], 2, v[4:5]
	v_subrev_u32_e32 v4, s48, v1
	v_ashrrev_i32_e32 v5, 31, v4
	v_lshlrev_b64 v[4:5], 15, v[4:5]
	v_lshl_add_u64 v[2:3], v[2:3], 0, v[4:5]
	v_add_co_u32_e32 v4, vcc, s30, v2
	s_nop 1
	v_addc_co_u32_e32 v5, vcc, 0, v3, vcc
	v_add_co_u32_e32 v6, vcc, s31, v2
	s_nop 1
	v_addc_co_u32_e32 v7, vcc, 0, v3, vcc
	v_add_co_u32_e32 v8, vcc, s33, v2
	s_nop 1
	v_addc_co_u32_e32 v9, vcc, 0, v3, vcc
	v_add_co_u32_e32 v10, vcc, s34, v2
	s_nop 1
	v_addc_co_u32_e32 v11, vcc, 0, v3, vcc
	v_add_co_u32_e32 v12, vcc, s35, v2
	s_nop 1
	v_addc_co_u32_e32 v13, vcc, 0, v3, vcc
	v_add_co_u32_e32 v14, vcc, s36, v2
	s_nop 1
	v_addc_co_u32_e32 v15, vcc, 0, v3, vcc
	v_add_co_u32_e32 v28, vcc, s38, v2
	s_nop 1
	v_addc_co_u32_e32 v29, vcc, 0, v3, vcc
	v_add_co_u32_e32 v30, vcc, s39, v2
	s_nop 1
	v_addc_co_u32_e32 v31, vcc, 0, v3, vcc
	v_add_co_u32_e32 v32, vcc, s40, v2
	s_nop 1
	v_addc_co_u32_e32 v33, vcc, 0, v3, vcc
	v_add_co_u32_e32 v34, vcc, s41, v2
	s_nop 1
	v_addc_co_u32_e32 v35, vcc, 0, v3, vcc
	v_add_co_u32_e32 v36, vcc, s42, v2
	s_nop 1
	v_addc_co_u32_e32 v37, vcc, 0, v3, vcc
	v_add_co_u32_e32 v38, vcc, s43, v2
	s_nop 1
	v_addc_co_u32_e32 v39, vcc, 0, v3, vcc
	v_add_co_u32_e32 v40, vcc, 0x340000, v2
	s_nop 1
	v_addc_co_u32_e32 v41, vcc, 0, v3, vcc
	v_add_co_u32_e32 v42, vcc, 0x380000, v2
	s_nop 1
	v_addc_co_u32_e32 v43, vcc, 0, v3, vcc
	v_add_co_u32_e32 v44, vcc, 0x3c0000, v2
	s_nop 1
	v_addc_co_u32_e32 v45, vcc, 0, v3, vcc
	global_load_dword v2, v[2:3], off nt
	s_nop 0
	global_load_dword v1, v[4:5], off nt
	s_nop 0
	global_load_dword v4, v[6:7], off nt
	global_load_dword v3, v[8:9], off nt
	s_nop 0
	global_load_dword v6, v[10:11], off nt
	global_load_dword v5, v[12:13], off nt
	global_load_dword v8, v[14:15], off nt
	global_load_dword v7, v[28:29], off nt
	s_nop 0
	global_load_dword v10, v[30:31], off nt
	global_load_dword v9, v[32:33], off nt
	global_load_dword v12, v[34:35], off nt
	global_load_dword v11, v[36:37], off nt
	global_load_dword v14, v[38:39], off nt
	global_load_dword v13, v[40:41], off nt
	global_load_dword v16, v[42:43], off nt
	global_load_dword v15, v[44:45], off nt
	s_branch .LBB0_25

.LBB0_40:
	s_waitcnt vmcnt(16)
	v_mov_b32_e32 v1, v208
	s_mov_b32 s31, s2
	s_barrier
	s_cmpk_gt_i32 s31, 0xaff
	s_cbranch_scc1 .LBB0_45
	s_ashr_i32 s4, s31, 31
	s_lshr_b32 s4, s4, 28
	s_add_i32 s4, s31, s4
	s_ashr_i32 s5, s4, 4
	s_and_b32 s4, s4, 0x1fffff0
	s_lshl_b32 s6, s5, 6
	s_sub_i32 s7, s31, s4
	s_bitcmp0_b32 s5, 1
	s_cselect_b32 s8, s11, s17
	s_cselect_b32 s9, s10, s16
	s_ashr_i32 s4, s6, 1
	s_and_b32 s4, s4, 0xffffff80
	s_ashr_i32 s5, s4, 31
	v_and_b32_e32 v20, 63, v1
	s_lshl_b64 s[4:5], s[4:5], 2
	s_add_u32 s4, s9, s4
	v_and_or_b32 v2, s6, 64, v20
	s_waitcnt vmcnt(13)
	v_ashrrev_i32_e32 v6, 6, v1
	s_addc_u32 s5, s8, s5
	s_waitcnt vmcnt(3)
	v_lshlrev_b32_e32 v16, 2, v2
	v_mov_b32_e32 v17, 0
	v_lshl_add_u64 v[2:3], s[4:5], 0, v[16:17]
	v_lshl_add_u32 v4, s7, 7, v6
	s_movk_i32 s8, 0x5800
	v_mad_i64_i32 v[2:3], s[4:5], v4, s8, v[2:3]
	s_mov_b32 s9, 0x2c000
	v_add_co_u32_e32 v26, vcc, s9, v2
	s_mov_b32 s12, 0x58000
	s_nop 0
	v_addc_co_u32_e32 v27, vcc, 0, v3, vcc
	v_add_co_u32_e32 v28, vcc, s12, v2
	s_mov_b32 s13, 0x84000
	s_nop 0
	v_addc_co_u32_e32 v29, vcc, 0, v3, vcc
	v_add_co_u32_e32 v30, vcc, s13, v2
	s_mov_b32 s28, 0xb0000
	s_nop 0
	v_addc_co_u32_e32 v31, vcc, 0, v3, vcc
	v_add_co_u32_e32 v32, vcc, s28, v2
	s_mov_b32 s29, 0xdc000
	s_nop 0
	v_addc_co_u32_e32 v33, vcc, 0, v3, vcc
	v_add_co_u32_e32 v34, vcc, s29, v2
	s_mov_b32 s30, 0x108000
	s_nop 0
	v_addc_co_u32_e32 v35, vcc, 0, v3, vcc
	v_add_co_u32_e32 v36, vcc, s30, v2
	s_mov_b32 s33, 0x134000
	s_nop 0
	v_addc_co_u32_e32 v37, vcc, 0, v3, vcc
	v_add_co_u32_e32 v38, vcc, s33, v2
	s_mov_b32 s34, 0x160000
	s_nop 0
	v_addc_co_u32_e32 v39, vcc, 0, v3, vcc
	v_add_co_u32_e32 v40, vcc, s34, v2
	s_mov_b32 s35, 0x18c000
	s_nop 0
	v_addc_co_u32_e32 v41, vcc, 0, v3, vcc
	v_add_co_u32_e32 v42, vcc, s35, v2
	s_mov_b32 s36, 0x1b8000
	s_nop 0
	v_addc_co_u32_e32 v43, vcc, 0, v3, vcc
	v_add_co_u32_e32 v44, vcc, s36, v2
	s_mov_b32 s37, 0x1e4000
	s_nop 0
	v_addc_co_u32_e32 v45, vcc, 0, v3, vcc
	v_add_co_u32_e32 v46, vcc, s37, v2
	s_mov_b32 s38, 0x210000
	s_nop 0
	v_addc_co_u32_e32 v47, vcc, 0, v3, vcc
	v_add_co_u32_e32 v48, vcc, s38, v2
	s_mov_b32 s4, 0x23c000
	s_nop 0
	v_addc_co_u32_e32 v49, vcc, 0, v3, vcc
	s_load_dword s6, s[62:63], 0x0
	s_load_dword s5, s[62:63], 0x10
	v_add_co_u32_e32 v50, vcc, s4, v2
	s_mov_b32 s4, 0x268000
	s_nop 0
	v_addc_co_u32_e32 v51, vcc, 0, v3, vcc
	v_add_co_u32_e32 v52, vcc, s4, v2
	s_mov_b32 s4, 0x294000
	s_nop 0
	v_addc_co_u32_e32 v53, vcc, 0, v3, vcc
	v_add_co_u32_e32 v54, vcc, s4, v2
	s_waitcnt lgkmcnt(0)
	s_lshr_b32 s4, s5, 16
	v_ashrrev_i32_e32 v21, 4, v1
	s_cmp_lg_u32 s4, 0
	v_lshlrev_b32_e32 v1, 3, v1
	s_cselect_b64 s[4:5], -1, 0
	v_and_b32_e32 v1, 0x78, v1
	s_cmp_lg_u64 s[4:5], 0
	v_lshlrev_b32_e32 v16, 1, v1
	s_addc_u32 s39, s6, 0
	v_lshl_add_u64 v[4:5], s[22:23], 0, v[16:17]
	s_mov_b64 s[4:5], 0x4378000
	v_lshl_add_u64 v[18:19], v[4:5], 0, s[4:5]
	s_movk_i32 s4, 0x104
	s_lshl_b32 s41, s39, 7
	v_addc_co_u32_e32 v55, vcc, 0, v3, vcc
	v_mul_lo_u32 v22, v6, s4
	v_mul_u32_u24_e32 v23, 0x104, v1
	v_add_u32_e32 v24, s41, v6
	global_load_dword v2, v[2:3], off nt
	s_nop 0
	global_load_dword v1, v[26:27], off nt
	global_load_dword v4, v[28:29], off nt
	global_load_dword v3, v[30:31], off nt
	global_load_dword v6, v[32:33], off nt
	global_load_dword v5, v[34:35], off nt
	global_load_dword v8, v[36:37], off nt
	global_load_dword v7, v[38:39], off nt
	global_load_dword v10, v[40:41], off nt
	global_load_dword v9, v[42:43], off nt
	global_load_dword v12, v[44:45], off nt
	global_load_dword v11, v[46:47], off nt
	global_load_dword v14, v[48:49], off nt
	global_load_dword v13, v[50:51], off nt
	global_load_dword v16, v[52:53], off nt
	global_load_dword v15, v[54:55], off nt
	s_lshl_b32 s40, s31, 7
	s_mov_b64 s[4:5], 0
	v_lshlrev_b32_e32 v25, 2, v20
	s_branch .LBB0_43

.LBB0_43:
	s_and_b64 s[6:7], s[4:5], exec
	s_cselect_b32 s6, 0x8200, 0
	s_add_i32 s43, s6, 0
	s_add_i32 s42, s39, s31
	s_cmpk_gt_i32 s42, 0xaff
	s_cselect_b64 s[6:7], -1, 0
	v_add3_u32 v26, s43, v25, v22
	s_and_b64 vcc, exec, s[6:7]
	s_waitcnt vmcnt(15)
	ds_write_b32 v26, v2
	s_waitcnt vmcnt(14)
	ds_write_b32 v26, v1 offset:2080
	s_waitcnt vmcnt(13)
	ds_write_b32 v26, v4 offset:4160
	s_waitcnt vmcnt(12)
	ds_write_b32 v26, v3 offset:6240
	s_waitcnt vmcnt(11)
	ds_write_b32 v26, v6 offset:8320
	s_waitcnt vmcnt(10)
	ds_write_b32 v26, v5 offset:10400
	s_waitcnt vmcnt(9)
	ds_write_b32 v26, v8 offset:12480
	s_waitcnt vmcnt(8)
	ds_write_b32 v26, v7 offset:14560
	s_waitcnt vmcnt(7)
	ds_write_b32 v26, v10 offset:16640
	s_waitcnt vmcnt(6)
	ds_write_b32 v26, v9 offset:18720
	s_waitcnt vmcnt(5)
	ds_write_b32 v26, v12 offset:20800
	s_waitcnt vmcnt(4)
	ds_write_b32 v26, v11 offset:22880
	s_waitcnt vmcnt(3)
	ds_write_b32 v26, v14 offset:24960
	s_waitcnt vmcnt(2)
	ds_write_b32 v26, v13 offset:27040
	s_waitcnt vmcnt(1)
	ds_write_b32 v26, v16 offset:29120
	s_waitcnt vmcnt(0)
	ds_write_b32 v26, v15 offset:31200
	s_cbranch_vccnz .LBB0_42
	s_ashr_i32 s44, s42, 31
	s_lshr_b32 s44, s44, 28
	s_add_i32 s44, s42, s44
	s_ashr_i32 s46, s44, 4
	s_lshl_b32 s47, s46, 6
	s_bitcmp0_b32 s46, 1
	s_cselect_b32 s48, s11, s17
	s_cselect_b32 s49, s10, s16
	s_ashr_i32 s44, s47, 1
	s_and_b32 s44, s44, 0xffffff80
	s_ashr_i32 s45, s44, 31
	s_lshl_b64 s[44:45], s[44:45], 2
	s_add_u32 s44, s49, s44
	v_and_or_b32 v1, s47, 64, v20
	s_addc_u32 s45, s48, s45
	v_lshlrev_b32_e32 v16, 2, v1
	v_lshl_add_u64 v[2:3], s[44:45], 0, v[16:17]
	v_add_u32_e32 v1, s40, v24
	s_lshl_b32 s44, s46, 11
	v_subrev_u32_e32 v1, s44, v1
	v_mad_i64_i32 v[2:3], s[44:45], v1, s8, v[2:3]
	v_add_co_u32_e32 v4, vcc, s9, v2
	s_nop 1
	v_addc_co_u32_e32 v5, vcc, 0, v3, vcc
	v_add_co_u32_e32 v6, vcc, s12, v2
	s_nop 1
	v_addc_co_u32_e32 v7, vcc, 0, v3, vcc
	v_add_co_u32_e32 v8, vcc, s13, v2
	s_nop 1
	v_addc_co_u32_e32 v9, vcc, 0, v3, vcc
	v_add_co_u32_e32 v10, vcc, s28, v2
	s_nop 1
	v_addc_co_u32_e32 v11, vcc, 0, v3, vcc
	v_add_co_u32_e32 v12, vcc, s29, v2
	s_nop 1
	v_addc_co_u32_e32 v13, vcc, 0, v3, vcc
	v_add_co_u32_e32 v14, vcc, s30, v2
	s_nop 1
	v_addc_co_u32_e32 v15, vcc, 0, v3, vcc
	v_add_co_u32_e32 v26, vcc, s33, v2
	s_nop 1
	v_addc_co_u32_e32 v27, vcc, 0, v3, vcc
	v_add_co_u32_e32 v28, vcc, s34, v2
	s_nop 1
	v_addc_co_u32_e32 v29, vcc, 0, v3, vcc
	v_add_co_u32_e32 v30, vcc, s35, v2
	s_nop 1
	v_addc_co_u32_e32 v31, vcc, 0, v3, vcc
	v_add_co_u32_e32 v32, vcc, s36, v2
	s_nop 1
	v_addc_co_u32_e32 v33, vcc, 0, v3, vcc
	v_add_co_u32_e32 v34, vcc, s37, v2
	s_nop 1
	v_addc_co_u32_e32 v35, vcc, 0, v3, vcc
	v_add_co_u32_e32 v36, vcc, s38, v2
	s_nop 1
	v_addc_co_u32_e32 v37, vcc, 0, v3, vcc
	v_add_co_u32_e32 v38, vcc, 0x23c000, v2
	s_nop 1
	v_addc_co_u32_e32 v39, vcc, 0, v3, vcc
	v_add_co_u32_e32 v40, vcc, 0x268000, v2
	s_nop 1
	v_addc_co_u32_e32 v41, vcc, 0, v3, vcc
	v_add_co_u32_e32 v42, vcc, 0x294000, v2
	s_nop 1
	v_addc_co_u32_e32 v43, vcc, 0, v3, vcc
	global_load_dword v2, v[2:3], off nt
	s_nop 0
	global_load_dword v1, v[4:5], off nt
	s_nop 0
	global_load_dword v4, v[6:7], off nt
	global_load_dword v3, v[8:9], off nt
	s_nop 0
	global_load_dword v6, v[10:11], off nt
	global_load_dword v5, v[12:13], off nt
	global_load_dword v8, v[14:15], off nt
	global_load_dword v7, v[26:27], off nt
	s_nop 0
	global_load_dword v10, v[28:29], off nt
	global_load_dword v9, v[30:31], off nt
	global_load_dword v12, v[32:33], off nt
	global_load_dword v11, v[34:35], off nt
	global_load_dword v14, v[36:37], off nt
	global_load_dword v13, v[38:39], off nt
	global_load_dword v16, v[40:41], off nt
	global_load_dword v15, v[42:43], off nt
	s_branch .LBB0_42

.LBB0_226:
	s_waitcnt vmcnt(0)
	s_barrier
	v_readlane_b32 s86, v255, 41
	s_cmp_lg_u32 s86, 1
	s_cbranch_scc1 .Ldc_w1_skip
	s_movk_i32 s87, 128
	s_cmp_gt_u32 s60, s87
	s_cselect_b32 s87, s87, 0
	s_cmp_lt_u32 s2, s87
	s_cbranch_scc1 .Ldc_w1_skip
	v_writelane_b32 v255, s24, 48
	v_writelane_b32 v255, s28, 49
	v_writelane_b32 v255, s29, 50
	v_writelane_b32 v255, s37, 51
	v_writelane_b32 v255, s40, 52
	v_writelane_b32 v255, s41, 53
	v_writelane_b32 v255, s42, 54
	v_writelane_b32 v255, s43, 55
	v_writelane_b32 v255, s44, 56
	v_writelane_b32 v255, s87, 47
	s_sub_u32 s2, s2, s87
	s_sub_u32 s60, s60, s87
	v_readlane_b32 s18, v255, 8
	v_readlane_b32 s19, v255, 9
	s_load_dwordx2 s[58:59], s[18:19], 0xe0
	s_nop 0
	s_load_dwordx2 s[18:19], s[18:19], 0xf0
	s_waitcnt lgkmcnt(0)
